# speedup vs baseline: 1.0079x; 1.0079x over previous
; __device__ __forceinline__ int opaque_tid() { int t = threadIdx.x; asm volatile("" : "+v"(t)); return t; }
; __device__ void attn_item(const Params& p, int layer, int item, int dry) {
;     ...
;   const int tid = opaque_tid(), wid = tid >> 6, lane = tid & 63, r = lane & 15, quad = lane >> 4;
;   bf16_t* cat = (bf16_t*)(ws + O_S + S_CAT);
;   const bf16_t* kv = (const bf16_t*)(ws + O_KV) + layer * 512;
;   const int tile = item >> 2, h = item & 3;
;   const int tok0 = tile * 128;
;   const int seq = tok0 < 32768 ? (tok0 >> 11) : 16 + ((tok0 - 32768) >> 12);
;   bf16_t* Ks = (bf16_t*)smem;
;   bf16_t* Vt = (bf16_t*)(smem + 256 * 72 * 2);
;   const bf16_t* kvs = kv + (size_t)seq * 256 * 1024;
;   for (int i = 0; i < 4; ++i) {
;     int idx = tid + 512 * i;
;     int m = idx >> 3, d0 = (idx & 7) * 8;
;     uint4 uk = *(const uint4*)(kvs + (size_t)m * 1024 + h * 64 + d0);
;     *(uint4*)(Ks + m * 72 + d0) = uk;
;     uint4 uv = *(const uint4*)(kvs + (size_t)m * 1024 + 256 + h * 64 + d0);
;     unsigned uu[4] = {uv.x, uv.y, uv.z, uv.w};
;     for (int j = 0; j < 8; ++j) Vt[(d0 + j) * 264 + m] = (bf16_t)((j & 1) ? (uu[j >> 1] >> 16) : (uu[j >> 1] & 0xffff));
;   }
;   __syncthreads();
;   const int t = tok0 + wid * 16 + r;
;   bf16_t* qp = cat + (size_t)t * 1024 + 768 + h * 64;
.LBB0_1348:
	s_and_b64 vcc, exec, s[4:5]
	s_cbranch_vccz .LBB0_1365
	s_lshl_b32 s4, s27, 5
	s_and_b32 s6, s4, 0xffffff80
	s_addk_i32 s4, 0x8000
	s_lshr_b32 s4, s4, 12
	s_ashr_i32 s5, s27, 6
	s_add_i32 s4, s4, 16
	s_cmp_lt_i32 s6, 0x8000
	s_waitcnt vmcnt(2)
	v_mov_b32_e32 v44, v208
	s_cselect_b32 s4, s5, s4
	s_ashr_i32 s5, s4, 31
	v_add_u32_e32 v10, 0x200, v44
	v_add_u32_e32 v18, 0x400, v44
	v_add_u32_e32 v26, 0x600, v44
	s_lshl_b64 s[4:5], s[4:5], 19
	s_waitcnt vmcnt(0)
	v_ashrrev_i32_e32 v34, 3, v44
	v_ashrrev_i32_e32 v36, 3, v10
	v_ashrrev_i32_e32 v38, 3, v18
	v_ashrrev_i32_e32 v40, 3, v26
	s_add_u32 s4, s77, s4
	v_ashrrev_i32_e32 v35, 31, v34
	v_ashrrev_i32_e32 v37, 31, v36
	v_ashrrev_i32_e32 v39, 31, v38
	v_ashrrev_i32_e32 v41, 31, v40
	s_addc_u32 s5, s78, s5
	v_lshlrev_b32_e32 v0, 3, v44
	v_lshlrev_b64 v[2:3], 11, v[34:35]
	s_lshl_b32 s7, s27, 7
	v_lshlrev_b64 v[10:11], 11, v[36:37]
	v_lshlrev_b64 v[18:19], 11, v[38:39]
	v_lshlrev_b64 v[26:27], 11, v[40:41]
	v_and_b32_e32 v42, 56, v0
	v_lshl_add_u64 v[2:3], s[4:5], 0, v[2:3]
	s_and_b32 s66, s7, 0x180
	v_lshl_add_u64 v[10:11], s[4:5], 0, v[10:11]
	v_lshl_add_u64 v[18:19], s[4:5], 0, v[18:19]
	v_lshl_add_u64 v[26:27], s[4:5], 0, v[26:27]
	v_lshlrev_b32_e32 v0, 1, v42
	v_lshl_add_u64 v[2:3], v[2:3], 0, s[66:67]
	v_lshl_add_u64 v[10:11], v[10:11], 0, s[66:67]
	v_lshl_add_u64 v[18:19], v[18:19], 0, s[66:67]
	v_lshl_add_u64 v[26:27], v[26:27], 0, s[66:67]
	v_lshl_add_u64 v[6:7], v[2:3], 0, v[0:1]
	v_lshl_add_u64 v[14:15], v[10:11], 0, v[0:1]
	v_lshl_add_u64 v[22:23], v[18:19], 0, v[0:1]
	v_lshl_add_u64 v[30:31], v[26:27], 0, v[0:1]
	global_load_dwordx4 v[2:5], v[6:7], off
	s_nop 0
	global_load_dwordx4 v[6:9], v[6:7], off offset:512
	s_nop 0
	global_load_dwordx4 v[10:13], v[14:15], off
	s_nop 0
	global_load_dwordx4 v[14:17], v[14:15], off offset:512
	s_nop 0
	global_load_dwordx4 v[18:21], v[22:23], off
	s_nop 0
	global_load_dwordx4 v[22:25], v[22:23], off offset:512
	s_nop 0
	global_load_dwordx4 v[26:29], v[30:31], off
	s_nop 0
	global_load_dwordx4 v[30:33], v[30:31], off offset:512
	s_movk_i32 s7, 0x90
	v_mul_u32_u24_e32 v41, 0x251, v42
	v_mad_u64_u32 v[42:43], s[4:5], v34, s7, v[0:1]
	v_lshl_add_u32 v43, v34, 1, v41
	v_mad_u64_u32 v[34:35], s[4:5], v36, s7, v[0:1]
	v_lshl_add_u32 v35, v36, 1, v41
	v_mad_u64_u32 v[36:37], s[4:5], v38, s7, v[0:1]
	v_lshl_add_u32 v37, v38, 1, v41
	v_mad_u64_u32 v[38:39], s[4:5], v40, s7, v[0:1]
	v_lshl_add_u32 v0, v40, 1, v41
	v_and_b32_e32 v60, 15, v44
	v_bfe_u32 v61, v44, 4, 2
	s_mov_b64 s[4:5], 0xe1a6600
	s_waitcnt vmcnt(7)
	ds_write_b128 v42, v[2:5]
	s_waitcnt vmcnt(6)
	ds_write_b16 v43, v6 offset:36864
	ds_write_b16_d16_hi v43, v6 offset:37456
	ds_write_b16 v43, v7 offset:38048
	ds_write_b16_d16_hi v43, v7 offset:38640
	ds_write_b16 v43, v8 offset:39232
	ds_write_b16_d16_hi v43, v8 offset:39824
	ds_write_b16 v43, v9 offset:40416
	ds_write_b16_d16_hi v43, v9 offset:41008
	s_waitcnt vmcnt(5)
	ds_write_b128 v34, v[10:13]
	s_waitcnt vmcnt(4)
	ds_write_b16 v35, v14 offset:36864
	ds_write_b16_d16_hi v35, v14 offset:37456
	ds_write_b16 v35, v15 offset:38048
	ds_write_b16_d16_hi v35, v15 offset:38640
	ds_write_b16 v35, v16 offset:39232
	ds_write_b16_d16_hi v35, v16 offset:39824
	ds_write_b16 v35, v17 offset:40416
	ds_write_b16_d16_hi v35, v17 offset:41008
	s_waitcnt vmcnt(3)
	ds_write_b128 v36, v[18:21]
	s_waitcnt vmcnt(2)
	ds_write_b16 v37, v22 offset:36864
	ds_write_b16_d16_hi v37, v22 offset:37456
	ds_write_b16 v37, v23 offset:38048
	ds_write_b16_d16_hi v37, v23 offset:38640
	ds_write_b16 v37, v24 offset:39232
	ds_write_b16_d16_hi v37, v24 offset:39824
	ds_write_b16 v37, v25 offset:40416
	ds_write_b16_d16_hi v37, v25 offset:41008
	s_waitcnt vmcnt(1)
	ds_write_b128 v38, v[26:29]
	s_waitcnt vmcnt(0)
	ds_write_b16 v0, v30 offset:36864
	ds_write_b16_d16_hi v0, v30 offset:37456
	ds_write_b16 v0, v31 offset:38048
	ds_write_b16_d16_hi v0, v31 offset:38640
	ds_write_b16 v0, v32 offset:39232
	ds_write_b16_d16_hi v0, v32 offset:39824
	ds_write_b16 v0, v33 offset:40416
	ds_write_b16_d16_hi v0, v33 offset:41008
	v_ashrrev_i32_e32 v0, 2, v44
	v_and_b32_e32 v0, -16, v0
	v_add_u32_e32 v0, s6, v0
	v_or_b32_e32 v2, v0, v60
	v_ashrrev_i32_e32 v3, 31, v2
	v_lshlrev_b64 v[2:3], 11, v[2:3]
	v_lshl_add_u64 v[2:3], s[14:15], 0, v[2:3]
	v_lshl_add_u64 v[2:3], v[2:3], 0, s[66:67]
	v_lshl_add_u64 v[54:55], v[2:3], 0, s[4:5]
	v_lshlrev_b32_e32 v0, 4, v61
	v_lshl_add_u64 v[34:35], v[54:55], 0, v[0:1]
	s_waitcnt lgkmcnt(0)
	s_barrier
; __device__ void attn_item(const Params& p, int layer, int item, int dry) {
;     ...
;   const int t = tok0 + wid * 16 + r;
;   bf16_t* qp = cat + (size_t)t * 1024 + 768 + h * 64;
;   bf16x8 qf[2];
;   qf[0] = *(const bf16x8*)(qp + quad * 8);
;   qf[1] = *(const bf16x8*)(qp + 32 + quad * 8);
;   f32x4 s[16];
;   for (int mt = 0; mt < 16; ++mt) {
;     s[mt] = f32x4{0.f, 0.f, 0.f, 0.f};
;     for (int ks = 0; ks < 2; ++ks) {
;       bf16x8 a = *(const bf16x8*)(Ks + (mt * 16 + r) * 72 + ks * 32 + quad * 8);
;       s[mt] = __builtin_amdgcn_mfma_f32_16x16x32_bf16(a, qf[ks], s[mt], 0, 0, 0);
;     }
;   }
;   float mx = -1e30f;
;   for (int mt = 0; mt < 16; ++mt)
;     for (int j = 0; j < 4; ++j) mx = fmaxf(mx, s[mt][j]);
;   mx = fmaxf(mx, __shfl_xor(mx, 16));
;   mx = fmaxf(mx, __shfl_xor(mx, 32));
	global_load_dwordx4 v[2:5], v[34:35], off
	global_load_dwordx4 v[56:59], v[34:35], off offset:64
	v_mad_u32_u24 v98, v60, s7, v0
	ds_read_b128 v[38:41], v98 offset:18432
	ds_read_b128 v[6:9], v98
	ds_read_b128 v[10:13], v98 offset:2304
	ds_read_b128 v[14:17], v98 offset:4608
	ds_read_b128 v[18:21], v98 offset:6912
	ds_read_b128 v[22:25], v98 offset:9216
	ds_read_b128 v[26:29], v98 offset:11520
	ds_read_b128 v[30:33], v98 offset:13824
	ds_read_b128 v[34:37], v98 offset:16128
	s_mov_b32 s4, 0xf149f2ca
	s_waitcnt vmcnt(1) lgkmcnt(8)
	v_mfma_f32_16x16x32_bf16 v[62:65], v[38:41], v[2:5], 0
	ds_read_b128 v[38:41], v98 offset:20736
	s_waitcnt lgkmcnt(0)
	v_mfma_f32_16x16x32_bf16 v[66:69], v[38:41], v[2:5], 0
	ds_read_b128 v[38:41], v98 offset:23040
	s_waitcnt lgkmcnt(0)
	v_mfma_f32_16x16x32_bf16 v[70:73], v[38:41], v[2:5], 0
	ds_read_b128 v[38:41], v98 offset:25344
	s_waitcnt lgkmcnt(0)
	v_mfma_f32_16x16x32_bf16 v[74:77], v[38:41], v[2:5], 0
	ds_read_b128 v[38:41], v98 offset:27648
	s_waitcnt lgkmcnt(0)
	v_mfma_f32_16x16x32_bf16 v[78:81], v[38:41], v[2:5], 0
	ds_read_b128 v[38:41], v98 offset:29952
	s_waitcnt lgkmcnt(0)
	v_mfma_f32_16x16x32_bf16 v[82:85], v[38:41], v[2:5], 0
	ds_read_b128 v[38:41], v98 offset:64
	v_mfma_f32_16x16x32_bf16 v[6:9], v[6:9], v[2:5], 0
	s_waitcnt vmcnt(0) lgkmcnt(0)
	v_mfma_f32_16x16x32_bf16 v[86:89], v[38:41], v[56:59], v[6:9]
	s_nop 5
	ds_read_b128 v[6:9], v98 offset:2368
	v_mfma_f32_16x16x32_bf16 v[10:13], v[10:13], v[2:5], 0
	s_waitcnt lgkmcnt(0)
	v_mfma_f32_16x16x32_bf16 v[90:93], v[6:9], v[56:59], v[10:13]
	ds_read_b128 v[6:9], v98 offset:4672
	v_mfma_f32_16x16x32_bf16 v[14:17], v[14:17], v[2:5], 0
	s_waitcnt lgkmcnt(0)
	v_mfma_f32_16x16x32_bf16 v[94:97], v[6:9], v[56:59], v[14:17]
	ds_read_b128 v[6:9], v98 offset:6976
	v_mfma_f32_16x16x32_bf16 v[18:21], v[18:21], v[2:5], 0
	s_waitcnt lgkmcnt(0)
	v_mfma_f32_16x16x32_bf16 v[50:53], v[6:9], v[56:59], v[18:21]
	ds_read_b128 v[6:9], v98 offset:9280
	v_mfma_f32_16x16x32_bf16 v[22:25], v[22:25], v[2:5], 0
	s_waitcnt lgkmcnt(0)
	v_mfma_f32_16x16x32_bf16 v[46:49], v[6:9], v[56:59], v[22:25]
	ds_read_b128 v[6:9], v98 offset:11584
	v_mfma_f32_16x16x32_bf16 v[26:29], v[26:29], v[2:5], 0
	s_waitcnt lgkmcnt(0)
	v_mfma_f32_16x16x32_bf16 v[42:45], v[6:9], v[56:59], v[26:29]
	ds_read_b128 v[6:9], v98 offset:13888
	v_mfma_f32_16x16x32_bf16 v[30:33], v[30:33], v[2:5], 0
	s_waitcnt lgkmcnt(0)
	v_mfma_f32_16x16x32_bf16 v[38:41], v[6:9], v[56:59], v[30:33]
	ds_read_b128 v[6:9], v98 offset:16192
	v_mfma_f32_16x16x32_bf16 v[34:37], v[34:37], v[2:5], 0
	s_waitcnt lgkmcnt(0)
	v_mfma_f32_16x16x32_bf16 v[34:37], v[6:9], v[56:59], v[34:37]
	ds_read_b128 v[6:9], v98 offset:18496
	s_waitcnt lgkmcnt(0)
	v_mfma_f32_16x16x32_bf16 v[30:33], v[6:9], v[56:59], v[62:65]
	ds_read_b128 v[6:9], v98 offset:20800
	s_nop 1
	ds_read_b128 v[62:65], v98 offset:32320
	s_waitcnt lgkmcnt(1)
	v_mfma_f32_16x16x32_bf16 v[26:29], v[6:9], v[56:59], v[66:69]
	ds_read_b128 v[6:9], v98 offset:23104
	s_waitcnt lgkmcnt(0)
	v_mfma_f32_16x16x32_bf16 v[22:25], v[6:9], v[56:59], v[70:73]
	ds_read_b128 v[6:9], v98 offset:25408
	s_waitcnt lgkmcnt(0)
	v_mfma_f32_16x16x32_bf16 v[18:21], v[6:9], v[56:59], v[74:77]
	ds_read_b128 v[6:9], v98 offset:27712
	s_waitcnt lgkmcnt(0)
	v_mfma_f32_16x16x32_bf16 v[14:17], v[6:9], v[56:59], v[78:81]
	ds_read_b128 v[6:9], v98 offset:30016
	s_waitcnt lgkmcnt(0)
	v_mfma_f32_16x16x32_bf16 v[10:13], v[6:9], v[56:59], v[82:85]
	ds_read_b128 v[6:9], v98 offset:32256
	s_waitcnt lgkmcnt(0)
	v_mfma_f32_16x16x32_bf16 v[6:9], v[6:9], v[2:5], 0
	v_mfma_f32_16x16x32_bf16 v[6:9], v[62:65], v[56:59], v[6:9]
	ds_read_b128 v[62:65], v98 offset:34560
	s_waitcnt lgkmcnt(0)
	v_mfma_f32_16x16x32_bf16 v[2:5], v[62:65], v[2:5], 0
	ds_read_b128 v[62:65], v98 offset:34624
	s_waitcnt lgkmcnt(0)
	v_mfma_f32_16x16x32_bf16 v[2:5], v[62:65], v[56:59], v[2:5]
	v_max3_f32 v56, v86, s4, v87
	v_max3_f32 v56, v56, v88, v89
	v_max3_f32 v56, v56, v90, v91
	v_max3_f32 v56, v56, v92, v93
	v_max3_f32 v56, v56, v94, v95
	v_max3_f32 v56, v56, v96, v97
	v_max3_f32 v56, v56, v50, v51
	v_max3_f32 v56, v56, v52, v53
	v_max3_f32 v56, v56, v46, v47
	v_max3_f32 v56, v56, v48, v49
	v_max3_f32 v56, v56, v42, v43
	v_max3_f32 v56, v56, v44, v45
	v_max3_f32 v56, v56, v38, v39
	v_max3_f32 v56, v56, v40, v41
	v_max3_f32 v56, v56, v34, v35
	v_max3_f32 v56, v56, v36, v37
	v_max3_f32 v56, v56, v30, v31
	v_max3_f32 v56, v56, v32, v33
	v_max3_f32 v56, v56, v26, v27
	v_max3_f32 v56, v56, v28, v29
	v_max3_f32 v56, v56, v22, v23
	v_max3_f32 v56, v56, v24, v25
	v_max3_f32 v56, v56, v18, v19
	v_max3_f32 v56, v56, v20, v21
	v_max3_f32 v56, v56, v14, v15
	v_max3_f32 v56, v56, v16, v17
	v_max3_f32 v56, v56, v10, v11
	v_max3_f32 v56, v56, v12, v13
	v_and_b32_e32 v58, 64, v228
	v_max3_f32 v56, v56, v6, v7
	v_xor_b32_e32 v57, 16, v228
	v_add_u32_e32 v59, 64, v58
	v_max3_f32 v56, v56, v8, v9
	v_cmp_lt_i32_e32 vcc, v57, v59
	v_max3_f32 v56, v56, v2, v3
	v_max3_f32 v56, v56, v4, v5
	v_cndmask_b32_e32 v57, v228, v57, vcc
	v_lshlrev_b32_e32 v58, 2, v57
	ds_bpermute_b32 v57, v58, v56
	s_movk_i32 s4, 0x210
	s_waitcnt lgkmcnt(0)
	v_max_f32_e32 v57, v57, v57
	v_max_f32_e32 v62, v56, v57
	v_xor_b32_e32 v56, 32, v228
	v_cmp_lt_i32_e32 vcc, v56, v59
	s_nop 1
	v_cndmask_b32_e32 v56, v228, v56, vcc
	v_lshlrev_b32_e32 v57, 2, v56
	ds_bpermute_b32 v59, v57, v62
	v_lshlrev_b32_e32 v56, 3, v61
	v_sub_u32_e32 v0, v0, v56
	s_andn2_b64 vcc, exec, s[24:25]
	s_waitcnt lgkmcnt(0)
; __device__ void attn_item(const Params& p, int layer, int item, int dry) {
;     ...
;   float sum = 0.f;
;   for (int mt = 0; mt < 16; ++mt)
;     for (int j = 0; j < 4; ++j) {
;       float e = __expf((s[mt][j] - mx) * 0.125f);
;       s[mt][j] = e;
;       sum += e;
;     }
;   sum += __shfl_xor(sum, 16);
;   sum += __shfl_xor(sum, 32);
	v_max_f32_e32 v59, v59, v59
	v_max_f32_e32 v59, v62, v59
	v_sub_f32_e32 v61, v86, v59
	v_mul_f32_e32 v61, 0x3e000000, v61
	v_mul_f32_e32 v61, 0x3fb8aa3b, v61
	v_exp_f32_e32 v65, v61
	v_sub_f32_e32 v61, v87, v59
	v_mul_f32_e32 v61, 0x3e000000, v61
	v_sub_f32_e32 v62, v90, v59
	v_mul_f32_e32 v61, 0x3fb8aa3b, v61
	v_mul_f32_e32 v62, 0x3e000000, v62
	v_exp_f32_e32 v66, v61
	v_sub_f32_e32 v61, v88, v59
	v_mul_f32_e32 v62, 0x3fb8aa3b, v62
	v_mul_f32_e32 v61, 0x3e000000, v61
	v_exp_f32_e32 v68, v62
	v_sub_f32_e32 v62, v91, v59
	v_mul_f32_e32 v61, 0x3fb8aa3b, v61
	v_mul_f32_e32 v62, 0x3e000000, v62
	v_exp_f32_e32 v67, v61
	v_sub_f32_e32 v61, v89, v59
	v_mul_f32_e32 v62, 0x3fb8aa3b, v62
	v_mul_f32_e32 v61, 0x3e000000, v61
	v_exp_f32_e32 v75, v62
	v_sub_f32_e32 v62, v92, v59
	v_mul_f32_e32 v61, 0x3fb8aa3b, v61
	v_mul_f32_e32 v62, 0x3e000000, v62
	v_exp_f32_e32 v74, v61
	v_mul_f32_e32 v62, 0x3fb8aa3b, v62
	v_add_f32_e32 v61, 0, v65
	v_exp_f32_e32 v69, v62
	v_sub_f32_e32 v62, v93, v59
	v_add_f32_e32 v61, v66, v61
	v_mul_f32_e32 v62, 0x3e000000, v62
	v_add_f32_e32 v61, v67, v61
	v_mul_f32_e32 v62, 0x3fb8aa3b, v62
	v_add_f32_e32 v61, v74, v61
	v_exp_f32_e32 v70, v62
	v_add_f32_e32 v61, v68, v61
	v_add_f32_e32 v61, v75, v61
	v_sub_f32_e32 v50, v50, v59
	v_add_f32_e32 v61, v69, v61
	v_mul_f32_e32 v50, 0x3e000000, v50
	v_add_f32_e32 v71, v70, v61
	v_sub_f32_e32 v61, v94, v59
	v_mul_f32_e32 v50, 0x3fb8aa3b, v50
	v_mul_f32_e32 v61, 0x3e000000, v61
	v_sub_f32_e32 v62, v95, v59
	v_exp_f32_e32 v90, v50
	v_sub_f32_e32 v50, v51, v59
	v_mul_f32_e32 v61, 0x3fb8aa3b, v61
	v_mul_f32_e32 v62, 0x3e000000, v62
	v_sub_f32_e32 v63, v96, v59
	v_mul_f32_e32 v50, 0x3e000000, v50
	v_exp_f32_e32 v61, v61
	v_mul_f32_e32 v62, 0x3fb8aa3b, v62
	v_mul_f32_e32 v63, 0x3e000000, v63
	v_sub_f32_e32 v64, v97, v59
	v_mul_f32_e32 v50, 0x3fb8aa3b, v50
	v_exp_f32_e32 v62, v62
	v_mul_f32_e32 v63, 0x3fb8aa3b, v63
	v_mul_f32_e32 v64, 0x3e000000, v64
	v_exp_f32_e32 v91, v50
	v_sub_f32_e32 v50, v52, v59
	v_exp_f32_e32 v63, v63
	v_mul_f32_e32 v64, 0x3fb8aa3b, v64
	v_mul_f32_e32 v50, 0x3e000000, v50
	v_exp_f32_e32 v64, v64
	v_mul_f32_e32 v50, 0x3fb8aa3b, v50
	v_add_f32_e32 v71, v61, v71
	v_exp_f32_e32 v92, v50
	v_sub_f32_e32 v50, v53, v59
	v_add_f32_e32 v71, v62, v71
	v_mul_f32_e32 v50, 0x3e000000, v50
	v_sub_f32_e32 v46, v46, v59
	v_add_f32_e32 v71, v63, v71
	v_mul_f32_e32 v50, 0x3fb8aa3b, v50
	v_mul_f32_e32 v46, 0x3e000000, v46
	v_sub_f32_e32 v47, v47, v59
	v_add_f32_e32 v71, v64, v71
	v_exp_f32_e32 v53, v50
	v_mul_f32_e32 v46, 0x3fb8aa3b, v46
	v_mul_f32_e32 v47, 0x3e000000, v47
	v_sub_f32_e32 v48, v48, v59
	v_add_f32_e32 v50, v90, v71
	v_exp_f32_e32 v46, v46
	v_mul_f32_e32 v47, 0x3fb8aa3b, v47
	v_mul_f32_e32 v48, 0x3e000000, v48
	v_sub_f32_e32 v49, v49, v59
	v_add_f32_e32 v50, v91, v50
	v_exp_f32_e32 v47, v47
	v_mul_f32_e32 v48, 0x3fb8aa3b, v48
	v_mul_f32_e32 v49, 0x3e000000, v49
	v_add_f32_e32 v50, v92, v50
	v_exp_f32_e32 v48, v48
	v_mul_f32_e32 v49, 0x3fb8aa3b, v49
	v_add_f32_e32 v50, v53, v50
	v_exp_f32_e32 v49, v49
	v_add_f32_e32 v50, v46, v50
	v_sub_f32_e32 v42, v42, v59
	v_add_f32_e32 v50, v47, v50
	v_mul_f32_e32 v42, 0x3e000000, v42
	v_add_f32_e32 v50, v48, v50
	v_mul_f32_e32 v42, 0x3fb8aa3b, v42
	v_add_f32_e32 v71, v49, v50
	v_exp_f32_e32 v50, v42
	v_sub_f32_e32 v42, v43, v59
	v_mul_f32_e32 v42, 0x3e000000, v42
	v_mul_f32_e32 v42, 0x3fb8aa3b, v42
	v_exp_f32_e32 v51, v42
	v_sub_f32_e32 v42, v44, v59
	v_mul_f32_e32 v42, 0x3e000000, v42
	v_mul_f32_e32 v42, 0x3fb8aa3b, v42
	v_exp_f32_e32 v52, v42
	v_sub_f32_e32 v42, v45, v59
	v_mul_f32_e32 v42, 0x3e000000, v42
	v_sub_f32_e32 v38, v38, v59
	v_mul_f32_e32 v42, 0x3fb8aa3b, v42
	v_mul_f32_e32 v38, 0x3e000000, v38
	v_sub_f32_e32 v39, v39, v59
	v_exp_f32_e32 v45, v42
	v_mul_f32_e32 v38, 0x3fb8aa3b, v38
	v_mul_f32_e32 v39, 0x3e000000, v39
	v_sub_f32_e32 v40, v40, v59
	v_add_f32_e32 v42, v50, v71
	v_exp_f32_e32 v38, v38
	v_mul_f32_e32 v39, 0x3fb8aa3b, v39
	v_mul_f32_e32 v40, 0x3e000000, v40
	v_sub_f32_e32 v41, v41, v59
	v_add_f32_e32 v42, v51, v42
	v_exp_f32_e32 v39, v39
	v_mul_f32_e32 v40, 0x3fb8aa3b, v40
	v_mul_f32_e32 v41, 0x3e000000, v41
	v_add_f32_e32 v42, v52, v42
	v_exp_f32_e32 v40, v40
	v_mul_f32_e32 v41, 0x3fb8aa3b, v41
	v_add_f32_e32 v42, v45, v42
	v_exp_f32_e32 v41, v41
	v_add_f32_e32 v42, v38, v42
	v_sub_f32_e32 v34, v34, v59
	v_add_f32_e32 v42, v39, v42
	v_mul_f32_e32 v34, 0x3e000000, v34
	v_add_f32_e32 v42, v40, v42
	v_mul_f32_e32 v34, 0x3fb8aa3b, v34
	v_add_f32_e32 v71, v41, v42
	v_exp_f32_e32 v42, v34
	v_sub_f32_e32 v34, v35, v59
	v_mul_f32_e32 v34, 0x3e000000, v34
	v_mul_f32_e32 v34, 0x3fb8aa3b, v34
	v_exp_f32_e32 v43, v34
	v_sub_f32_e32 v34, v36, v59
	v_mul_f32_e32 v34, 0x3e000000, v34
	v_mul_f32_e32 v34, 0x3fb8aa3b, v34
	v_exp_f32_e32 v44, v34
	v_sub_f32_e32 v34, v37, v59
	v_mul_f32_e32 v34, 0x3e000000, v34
	v_sub_f32_e32 v30, v30, v59
	v_mul_f32_e32 v34, 0x3fb8aa3b, v34
	v_mul_f32_e32 v30, 0x3e000000, v30
	v_sub_f32_e32 v31, v31, v59
	v_exp_f32_e32 v37, v34
	v_mul_f32_e32 v30, 0x3fb8aa3b, v30
	v_mul_f32_e32 v31, 0x3e000000, v31
	v_sub_f32_e32 v32, v32, v59
	v_add_f32_e32 v34, v42, v71
	v_exp_f32_e32 v30, v30
	v_mul_f32_e32 v31, 0x3fb8aa3b, v31
	v_mul_f32_e32 v32, 0x3e000000, v32
	v_sub_f32_e32 v33, v33, v59
	v_add_f32_e32 v34, v43, v34
	v_exp_f32_e32 v31, v31
	v_mul_f32_e32 v32, 0x3fb8aa3b, v32
	v_mul_f32_e32 v33, 0x3e000000, v33
	v_add_f32_e32 v34, v44, v34
	v_exp_f32_e32 v32, v32
	v_mul_f32_e32 v33, 0x3fb8aa3b, v33
	v_add_f32_e32 v34, v37, v34
	v_exp_f32_e32 v33, v33
	v_add_f32_e32 v34, v30, v34
	v_sub_f32_e32 v26, v26, v59
	v_add_f32_e32 v34, v31, v34
	v_mul_f32_e32 v26, 0x3e000000, v26
	v_add_f32_e32 v34, v32, v34
; __device__ __forceinline__ unsigned short f2bf(float f) { return (unsigned short)(pack2(f, 0.f) & 0xffffu); }
; __device__ void attn_item(const Params& p, int layer, int item, int dry) {
;     ...
;   for (int mt = 0; mt < 16; ++mt)
;     for (int j = 0; j < 4; ++j) {
;       float e = __expf((s[mt][j] - mx) * 0.125f);
;       s[mt][j] = e;
;       sum += e;
;     }
;   sum += __shfl_xor(sum, 16);
;   sum += __shfl_xor(sum, 32);
;   const float inv = 1.f / sum;
;   f32x4 o[4] = {};
;   for (int ks = 0; ks < 8; ++ks) {
;     bf16x8 pb;
;     for (int j = 0; j < 4; ++j) {
;       pb[j] = (short)f2bf(s[2 * ks][j]);
;       pb[4 + j] = (short)f2bf(s[2 * ks + 1][j]);
;     }
;     for (int dt = 0; dt < 4; ++dt) {
;       const bf16_t* vp = Vt + (dt * 16 + r) * 264 + ks * 32 + quad * 4;
;       uint2 v0 = *(const uint2*)vp, v1 = *(const uint2*)(vp + 16);
;       bf16x8 av;
;       av[0] = (short)(v0.x & 0xffff); av[1] = (short)(v0.x >> 16); av[2] = (short)(v0.y & 0xffff); av[3] = (short)(v0.y >> 16);
;       av[4] = (short)(v1.x & 0xffff); av[5] = (short)(v1.x >> 16); av[6] = (short)(v1.y & 0xffff); av[7] = (short)(v1.y >> 16);
;       o[dt] = __builtin_amdgcn_mfma_f32_16x16x32_bf16(av, pb, o[dt], 0, 0, 0);
	v_mul_f32_e32 v26, 0x3fb8aa3b, v26
	v_add_f32_e32 v71, v33, v34
	v_exp_f32_e32 v34, v26
	v_sub_f32_e32 v26, v27, v59
	v_mul_f32_e32 v26, 0x3e000000, v26
	v_mul_f32_e32 v26, 0x3fb8aa3b, v26
	v_exp_f32_e32 v35, v26
	v_sub_f32_e32 v26, v28, v59
	v_mul_f32_e32 v26, 0x3e000000, v26
	v_mul_f32_e32 v26, 0x3fb8aa3b, v26
	v_exp_f32_e32 v28, v26
	v_sub_f32_e32 v26, v29, v59
	v_mul_f32_e32 v26, 0x3e000000, v26
	v_sub_f32_e32 v22, v22, v59
	v_mul_f32_e32 v26, 0x3fb8aa3b, v26
	v_mul_f32_e32 v22, 0x3e000000, v22
	v_sub_f32_e32 v23, v23, v59
	v_exp_f32_e32 v36, v26
	v_mul_f32_e32 v22, 0x3fb8aa3b, v22
	v_mul_f32_e32 v23, 0x3e000000, v23
	v_sub_f32_e32 v24, v24, v59
	v_add_f32_e32 v26, v34, v71
	v_exp_f32_e32 v22, v22
	v_mul_f32_e32 v23, 0x3fb8aa3b, v23
	v_mul_f32_e32 v24, 0x3e000000, v24
	v_sub_f32_e32 v25, v25, v59
	v_add_f32_e32 v26, v35, v26
	v_exp_f32_e32 v23, v23
	v_mul_f32_e32 v24, 0x3fb8aa3b, v24
	v_mul_f32_e32 v25, 0x3e000000, v25
	v_add_f32_e32 v26, v28, v26
	v_exp_f32_e32 v24, v24
	v_mul_f32_e32 v25, 0x3fb8aa3b, v25
	v_add_f32_e32 v26, v36, v26
	v_exp_f32_e32 v25, v25
	v_add_f32_e32 v26, v22, v26
	v_sub_f32_e32 v18, v18, v59
	v_sub_f32_e32 v20, v20, v59
	v_add_f32_e32 v26, v23, v26
	v_mul_f32_e32 v18, 0x3e000000, v18
	v_sub_f32_e32 v19, v19, v59
	v_mul_f32_e32 v20, 0x3e000000, v20
	v_add_f32_e32 v26, v24, v26
	v_mul_f32_e32 v18, 0x3fb8aa3b, v18
	v_mul_f32_e32 v19, 0x3e000000, v19
	v_mul_f32_e32 v20, 0x3fb8aa3b, v20
	v_add_f32_e32 v29, v25, v26
	v_exp_f32_e32 v18, v18
	v_mul_f32_e32 v19, 0x3fb8aa3b, v19
	v_exp_f32_e32 v26, v20
	v_sub_f32_e32 v20, v21, v59
	v_exp_f32_e32 v19, v19
	v_mul_f32_e32 v20, 0x3e000000, v20
	v_sub_f32_e32 v14, v14, v59
	v_mul_f32_e32 v20, 0x3fb8aa3b, v20
	v_mul_f32_e32 v14, 0x3e000000, v14
	v_sub_f32_e32 v15, v15, v59
	v_exp_f32_e32 v27, v20
	v_mul_f32_e32 v14, 0x3fb8aa3b, v14
	v_mul_f32_e32 v15, 0x3e000000, v15
	v_sub_f32_e32 v16, v16, v59
	v_add_f32_e32 v20, v18, v29
	v_exp_f32_e32 v14, v14
	v_mul_f32_e32 v15, 0x3fb8aa3b, v15
	v_mul_f32_e32 v16, 0x3e000000, v16
	v_sub_f32_e32 v17, v17, v59
	v_add_f32_e32 v20, v19, v20
	v_exp_f32_e32 v15, v15
	v_mul_f32_e32 v16, 0x3fb8aa3b, v16
	v_mul_f32_e32 v17, 0x3e000000, v17
	v_sub_f32_e32 v10, v10, v59
	v_add_f32_e32 v20, v26, v20
	v_exp_f32_e32 v16, v16
	v_mul_f32_e32 v17, 0x3fb8aa3b, v17
	v_mul_f32_e32 v10, 0x3e000000, v10
	v_sub_f32_e32 v11, v11, v59
	v_add_f32_e32 v20, v27, v20
	v_exp_f32_e32 v17, v17
	v_mul_f32_e32 v10, 0x3fb8aa3b, v10
	v_mul_f32_e32 v11, 0x3e000000, v11
	v_sub_f32_e32 v12, v12, v59
	v_add_f32_e32 v20, v14, v20
	v_exp_f32_e32 v10, v10
	v_mul_f32_e32 v11, 0x3fb8aa3b, v11
	v_mul_f32_e32 v12, 0x3e000000, v12
	v_sub_f32_e32 v13, v13, v59
	v_add_f32_e32 v20, v15, v20
	v_exp_f32_e32 v11, v11
	v_mul_f32_e32 v12, 0x3fb8aa3b, v12
	v_mul_f32_e32 v13, 0x3e000000, v13
	v_add_f32_e32 v20, v16, v20
	v_exp_f32_e32 v12, v12
	v_mul_f32_e32 v13, 0x3fb8aa3b, v13
	v_add_f32_e32 v20, v17, v20
	v_exp_f32_e32 v13, v13
	v_add_f32_e32 v20, v10, v20
	v_add_f32_e32 v20, v11, v20
	v_add_f32_e32 v20, v12, v20
	v_add_f32_e32 v86, v13, v20
	v_sub_f32_e32 v7, v7, v59
	v_mul_u32_u24_e32 v176, 0x250, v60
	v_lshrrev_b32_e32 v177, 3, v60
	v_add_u32_e32 v20, v176, v0
	v_lshl_add_u32 v20, v177, 3, v20
	v_mul_f32_e32 v29, 0x3e000000, v7
	v_add_u32_e32 v21, 0x9000, v20
	v_add_u32_e32 v7, 0xb410, v20
	v_add_u32_e32 v0, 0xd820, v20
	v_add_u32_e32 v20, 0xfc30, v20
	v_cvt_pk_bf16_f32 v69, v69, v70
	ds_read2_b64 v[70:73], v21 offset1:4
	v_cvt_pk_bf16_f32 v68, v68, v75
	v_cvt_pk_bf16_f32 v67, v67, v74
	ds_read2_b64 v[74:77], v7 offset0:32 offset1:36
	ds_read2_b64 v[78:81], v0 offset0:64 offset1:68
	ds_read2_b64 v[82:85], v20 offset0:96 offset1:100
	v_sub_f32_e32 v6, v6, v59
	v_mul_f32_e32 v6, 0x3e000000, v6
	v_mul_f32_e32 v6, 0x3fb8aa3b, v6
	v_exp_f32_e32 v6, v6
	s_waitcnt lgkmcnt(3)
	v_bfi_b32 v72, s65, v72, v72
	s_waitcnt lgkmcnt(2)
	v_bfi_b32 v76, s65, v76, v76
	s_waitcnt lgkmcnt(1)
	v_bfi_b32 v80, s65, v80, v80
	v_mul_f32_e32 v29, 0x3fb8aa3b, v29
	s_waitcnt lgkmcnt(0)
	v_bfi_b32 v84, s65, v84, v84
	v_exp_f32_e32 v29, v29
	v_cvt_pk_bf16_f32 v66, v65, v66
	v_add_f32_e32 v60, v6, v86
	ds_read2_b64 v[86:89], v21 offset0:8 offset1:12
	v_mfma_f32_16x16x32_bf16 v[70:73], v[70:73], v[66:69], 0
	v_add_f32_e32 v94, v29, v60
	v_sub_f32_e32 v8, v8, v59
	v_mul_f32_e32 v8, 0x3e000000, v8
	v_mfma_f32_16x16x32_bf16 v[74:77], v[74:77], v[66:69], 0
	s_waitcnt lgkmcnt(0)
	v_bfi_b32 v88, s65, v88, v88
	v_mul_f32_e32 v8, 0x3fb8aa3b, v8
	v_sub_f32_e32 v2, v2, v59
	v_mfma_f32_16x16x32_bf16 v[78:81], v[78:81], v[66:69], 0
	v_mul_f32_e32 v2, 0x3e000000, v2
	v_mul_f32_e32 v2, 0x3fb8aa3b, v2
	v_cvt_pk_bf16_f32 v27, v26, v27
	v_mfma_f32_16x16x32_bf16 v[66:69], v[82:85], v[66:69], 0
	v_cvt_pk_bf16_f32 v83, v63, v64
	v_cvt_pk_bf16_f32 v82, v61, v62
	ds_read2_b64 v[60:63], v0 offset0:72 offset1:76
	v_cvt_pk_bf16_f32 v85, v92, v53
	v_cvt_pk_bf16_f32 v84, v90, v91
	ds_read2_b64 v[90:93], v7 offset0:40 offset1:44
	v_cvt_pk_bf16_f32 v53, v52, v45
	s_waitcnt lgkmcnt(1)
	v_bfi_b32 v62, s65, v62, v62
	v_mfma_f32_16x16x32_bf16 v[70:73], v[86:89], v[82:85], v[70:73]
	ds_read2_b64 v[86:89], v20 offset0:104 offset1:108
	v_cvt_pk_bf16_f32 v52, v50, v51
	v_cvt_pk_bf16_f32 v51, v48, v49
	v_mfma_f32_16x16x32_bf16 v[60:63], v[60:63], v[82:85], v[78:81]
	v_cvt_pk_bf16_f32 v50, v46, v47
	ds_read2_b64 v[46:49], v0 offset0:80 offset1:84
	s_waitcnt lgkmcnt(2)
	v_bfi_b32 v92, s65, v92, v92
	ds_read2_b64 v[78:81], v21 offset0:16 offset1:20
	s_waitcnt lgkmcnt(2)
	v_bfi_b32 v88, s65, v88, v88
	v_mfma_f32_16x16x32_bf16 v[74:77], v[90:93], v[82:85], v[74:77]
	s_waitcnt lgkmcnt(0)
; __device__ __forceinline__ unsigned short f2bf(float f) { return (unsigned short)(pack2(f, 0.f) & 0xffffu); }
; __device__ void attn_item(const Params& p, int layer, int item, int dry) {
;     ...
;   sum += __shfl_xor(sum, 16);
;   sum += __shfl_xor(sum, 32);
;   const float inv = 1.f / sum;
;   f32x4 o[4] = {};
;   for (int ks = 0; ks < 8; ++ks) {
;     bf16x8 pb;
;     for (int j = 0; j < 4; ++j) {
;       pb[j] = (short)f2bf(s[2 * ks][j]);
;       pb[4 + j] = (short)f2bf(s[2 * ks + 1][j]);
;     }
;     for (int dt = 0; dt < 4; ++dt) {
;       const bf16_t* vp = Vt + (dt * 16 + r) * 264 + ks * 32 + quad * 4;
;       uint2 v0 = *(const uint2*)vp, v1 = *(const uint2*)(vp + 16);
;       bf16x8 av;
;       av[0] = (short)(v0.x & 0xffff); av[1] = (short)(v0.x >> 16); av[2] = (short)(v0.y & 0xffff); av[3] = (short)(v0.y >> 16);
;       av[4] = (short)(v1.x & 0xffff); av[5] = (short)(v1.x >> 16); av[6] = (short)(v1.y & 0xffff); av[7] = (short)(v1.y >> 16);
;       o[dt] = __builtin_amdgcn_mfma_f32_16x16x32_bf16(av, pb, o[dt], 0, 0, 0);
;     }
;   }
;   for (int dt = 0; dt < 4; ++dt) {
;     uint2 ov;
;     ov.x = pack2(o[dt][0] * inv, o[dt][1] * inv);
;     ov.y = pack2(o[dt][2] * inv, o[dt][3] * inv);
;     if (!dry) *(uint2*)(qp + dt * 16 + quad * 4) = ov;
;   }
	v_bfi_b32 v80, s65, v80, v80
	v_bfi_b32 v48, s65, v48, v48
	v_cvt_pk_bf16_f32 v45, v44, v37
	v_mfma_f32_16x16x32_bf16 v[64:67], v[86:89], v[82:85], v[66:69]
	ds_read2_b64 v[82:85], v7 offset0:48 offset1:52
	v_cvt_pk_bf16_f32 v44, v42, v43
	v_cvt_pk_bf16_f32 v43, v40, v41
	v_mfma_f32_16x16x32_bf16 v[68:71], v[78:81], v[50:53], v[70:73]
	ds_read2_b64 v[78:81], v20 offset0:112 offset1:116
	v_cvt_pk_bf16_f32 v42, v38, v39
	ds_read2_b64 v[38:41], v0 offset0:88 offset1:92
	v_mfma_f32_16x16x32_bf16 v[46:49], v[46:49], v[50:53], v[60:63]
	s_waitcnt lgkmcnt(2)
	v_bfi_b32 v84, s65, v84, v84
	s_waitcnt lgkmcnt(1)
	v_bfi_b32 v80, s65, v80, v80
	v_cvt_pk_bf16_f32 v37, v28, v36
	ds_read2_b64 v[60:63], v21 offset0:24 offset1:28
	s_waitcnt lgkmcnt(1)
	v_bfi_b32 v40, s65, v40, v40
	v_mfma_f32_16x16x32_bf16 v[72:75], v[82:85], v[50:53], v[74:77]
	v_cvt_pk_bf16_f32 v36, v34, v35
	v_cvt_pk_bf16_f32 v35, v32, v33
	s_waitcnt lgkmcnt(0)
	v_bfi_b32 v62, s65, v62, v62
	v_mfma_f32_16x16x32_bf16 v[50:53], v[78:81], v[50:53], v[64:67]
	v_cvt_pk_bf16_f32 v34, v30, v31
	ds_read2_b64 v[30:33], v0 offset0:96 offset1:100
	v_exp_f32_e32 v90, v8
	ds_read2_b64 v[64:67], v7 offset0:56 offset1:60
	v_mfma_f32_16x16x32_bf16 v[60:63], v[60:63], v[42:45], v[68:71]
	v_sub_f32_e32 v8, v9, v59
	s_waitcnt lgkmcnt(1)
	v_bfi_b32 v32, s65, v32, v32
	v_mul_f32_e32 v8, 0x3e000000, v8
	ds_read2_b64 v[68:71], v20 offset0:120 offset1:124
	v_mfma_f32_16x16x32_bf16 v[38:41], v[38:41], v[42:45], v[46:49]
	s_waitcnt lgkmcnt(1)
	v_bfi_b32 v66, s65, v66, v66
	v_mul_f32_e32 v8, 0x3fb8aa3b, v8
	v_exp_f32_e32 v9, v2
	ds_read2_b64 v[46:49], v21 offset0:32 offset1:36
	s_waitcnt lgkmcnt(1)
	v_bfi_b32 v70, s65, v70, v70
	v_mfma_f32_16x16x32_bf16 v[64:67], v[64:67], v[42:45], v[72:75]
	v_sub_f32_e32 v2, v3, v59
	v_exp_f32_e32 v76, v8
	s_waitcnt lgkmcnt(0)
	v_bfi_b32 v48, s65, v48, v48
	v_mfma_f32_16x16x32_bf16 v[42:45], v[68:71], v[42:45], v[50:53]
	v_mul_f32_e32 v2, 0x3e000000, v2
	v_mul_f32_e32 v2, 0x3fb8aa3b, v2
	v_exp_f32_e32 v28, v2
	ds_read2_b64 v[50:53], v7 offset0:64 offset1:68
	v_mfma_f32_16x16x32_bf16 v[46:49], v[46:49], v[34:37], v[60:63]
	v_add_f32_e32 v8, v90, v94
	v_add_f32_e32 v8, v76, v8
	v_add_f32_e32 v2, v9, v8
	ds_read2_b64 v[60:63], v20 offset0:128 offset1:132
	v_mfma_f32_16x16x32_bf16 v[30:33], v[30:33], v[34:37], v[38:41]
	s_waitcnt lgkmcnt(1)
	v_bfi_b32 v52, s65, v52, v52
	v_add_f32_e32 v8, v28, v2
	v_sub_f32_e32 v2, v4, v59
	ds_read2_b64 v[38:41], v21 offset0:40 offset1:44
	s_waitcnt lgkmcnt(1)
	v_bfi_b32 v62, s65, v62, v62
	v_mfma_f32_16x16x32_bf16 v[50:53], v[50:53], v[34:37], v[64:67]
	v_mul_f32_e32 v2, 0x3e000000, v2
	v_mul_f32_e32 v2, 0x3fb8aa3b, v2
	s_waitcnt lgkmcnt(0)
	v_bfi_b32 v40, s65, v40, v40
	v_mfma_f32_16x16x32_bf16 v[34:37], v[60:63], v[34:37], v[42:45]
	ds_read2_b64 v[60:63], v0 offset0:104 offset1:108
	v_cvt_pk_bf16_f32 v26, v18, v19
	v_cvt_pk_bf16_f32 v25, v24, v25
	v_cvt_pk_bf16_f32 v24, v22, v23
	v_exp_f32_e32 v18, v2
	v_sub_f32_e32 v19, v5, v59
	ds_read2_b64 v[2:5], v21 offset0:48 offset1:52
	ds_read2_b64 v[42:45], v7 offset0:72 offset1:76
	v_mfma_f32_16x16x32_bf16 v[38:41], v[38:41], v[24:27], v[46:49]
	v_cvt_pk_bf16_f32 v13, v12, v13
	v_cvt_pk_bf16_f32 v12, v10, v11
	v_cvt_pk_bf16_f32 v11, v16, v17
	ds_read2_b64 v[46:49], v20 offset0:136 offset1:140
	v_cvt_pk_bf16_f32 v10, v14, v15
	ds_read2_b64 v[14:17], v0 offset0:112 offset1:116
	s_waitcnt lgkmcnt(4)
	v_bfi_b32 v62, s65, v62, v62
	s_waitcnt lgkmcnt(3)
	v_bfi_b32 v4, s65, v4, v4
	s_waitcnt lgkmcnt(2)
	v_bfi_b32 v44, s65, v44, v44
	s_waitcnt lgkmcnt(1)
	v_bfi_b32 v48, s65, v48, v48
	s_waitcnt lgkmcnt(0)
	v_bfi_b32 v16, s65, v16, v16
	v_mfma_f32_16x16x32_bf16 v[30:33], v[60:63], v[24:27], v[30:33]
	v_mul_f32_e32 v19, 0x3e000000, v19
	v_mul_f32_e32 v19, 0x3fb8aa3b, v19
	v_exp_f32_e32 v19, v19
	v_mfma_f32_16x16x32_bf16 v[2:5], v[2:5], v[10:13], v[38:41]
	v_add_f32_e32 v8, v18, v8
	s_nop 1
	ds_read2_b64 v[38:41], v20 offset0:144 offset1:148
	v_mfma_f32_16x16x32_bf16 v[42:45], v[42:45], v[24:27], v[50:53]
	s_waitcnt lgkmcnt(0)
	v_bfi_b32 v40, s65, v40, v40
	v_mfma_f32_16x16x32_bf16 v[22:25], v[46:49], v[24:27], v[34:37]
	s_nop 2
	ds_read2_b64 v[34:37], v7 offset0:80 offset1:84
	v_mfma_f32_16x16x32_bf16 v[14:17], v[14:17], v[10:13], v[30:33]
	s_waitcnt lgkmcnt(0)
	v_bfi_b32 v36, s65, v36, v36
	s_nop 0
	ds_read2_b64 v[30:33], v21 offset0:56 offset1:60
	v_mfma_f32_16x16x32_bf16 v[22:25], v[38:41], v[10:13], v[22:25]
	v_cvt_pk_bf16_f32 v41, v18, v19
	v_cvt_pk_bf16_f32 v40, v9, v28
	v_cvt_pk_bf16_f32 v39, v90, v76
	s_waitcnt lgkmcnt(0)
	v_bfi_b32 v32, s65, v32, v32
	v_cvt_pk_bf16_f32 v38, v6, v29
	v_mfma_f32_16x16x32_bf16 v[34:37], v[34:37], v[10:13], v[42:45]
	v_add_f32_e32 v21, v19, v8
	ds_read2_b64 v[8:11], v7 offset0:88 offset1:92
	ds_read2_b64 v[26:29], v0 offset0:120 offset1:124
	v_mfma_f32_16x16x32_bf16 v[2:5], v[30:33], v[38:41], v[2:5]
	ds_read2_b64 v[30:33], v20 offset0:152 offset1:156
	ds_bpermute_b32 v0, v58, v21
	s_waitcnt lgkmcnt(3)
	v_bfi_b32 v10, s65, v10, v10
	s_waitcnt lgkmcnt(2)
	v_bfi_b32 v28, s65, v28, v28
	s_waitcnt lgkmcnt(1)
	v_bfi_b32 v32, s65, v32, v32
	s_waitcnt lgkmcnt(0)
	v_add_f32_e32 v0, v21, v0
	ds_bpermute_b32 v18, v57, v0
	v_mfma_f32_16x16x32_bf16 v[6:9], v[8:11], v[38:41], v[34:37]
	v_mfma_f32_16x16x32_bf16 v[10:13], v[26:29], v[38:41], v[14:17]
	v_mfma_f32_16x16x32_bf16 v[14:17], v[30:33], v[38:41], v[22:25]
	s_cbranch_vccnz .LBB0_1351
	s_waitcnt lgkmcnt(0)
	v_add_f32_e32 v0, v0, v18
	v_div_scale_f32 v18, s[4:5], v0, v0, 1.0
	v_rcp_f32_e32 v19, v18
	v_mov_b32_e32 v57, v1
	v_lshl_add_u64 v[20:21], v[54:55], 0, v[56:57]
	v_fma_f32 v22, -v18, v19, 1.0
	v_fmac_f32_e32 v19, v22, v19
	v_div_scale_f32 v22, vcc, 1.0, v0, 1.0
	v_mul_f32_e32 v23, v22, v19
	v_fma_f32 v24, -v18, v23, v22
	v_fmac_f32_e32 v23, v24, v19
	v_fma_f32 v18, -v18, v23, v22
	v_div_fmas_f32 v18, v18, v19, v23
	v_div_fixup_f32 v0, v18, v0, 1.0
	v_pk_mul_f32 v[4:5], v[0:1], v[4:5] op_sel_hi:[0,1]
	v_pk_mul_f32 v[2:3], v[0:1], v[2:3] op_sel_hi:[0,1]
	v_cvt_pk_bf16_f32 v5, v4, v5
	v_cvt_pk_bf16_f32 v4, v2, v3
	global_store_dwordx2 v[20:21], v[4:5], off
	v_pk_mul_f32 v[2:3], v[0:1], v[8:9] op_sel_hi:[0,1]
	v_pk_mul_f32 v[4:5], v[0:1], v[6:7] op_sel_hi:[0,1]
	v_cvt_pk_bf16_f32 v3, v2, v3
	v_cvt_pk_bf16_f32 v2, v4, v5
	global_store_dwordx2 v[20:21], v[2:3], off offset:32
	v_pk_mul_f32 v[2:3], v[0:1], v[12:13] op_sel_hi:[0,1]
	v_pk_mul_f32 v[4:5], v[0:1], v[10:11] op_sel_hi:[0,1]
	v_cvt_pk_bf16_f32 v3, v2, v3
	v_cvt_pk_bf16_f32 v2, v4, v5
	global_store_dwordx2 v[20:21], v[2:3], off offset:64
	v_pk_mul_f32 v[2:3], v[0:1], v[16:17] op_sel_hi:[0,1]
	v_pk_mul_f32 v[4:5], v[0:1], v[14:15] op_sel_hi:[0,1]
	v_cvt_pk_bf16_f32 v3, v2, v3
	v_cvt_pk_bf16_f32 v2, v4, v5
	global_store_dwordx2 v[20:21], v[2:3], off offset:96
